# scan XCD map + compute rewrite, without the deeper staging prefetch
# speedup vs baseline: 1.0067x; 1.0067x over previous
.LBB0_626:
	s_or_b64 exec, exec, s[0:1]
	v_lshlrev_b32_e32 v4, 16, v67
	v_mul_f32_e32 v4, 0xbfb8aa3b, v4
	v_exp_f32_e32 v4, v4
	s_or_b32 s0, s30, 7
	v_lshlrev_b32_e32 v0, 16, v31
	v_lshlrev_b32_e32 v2, 16, v70
	v_mul_f32_e32 v0, v41, v0
	v_add_f32_e32 v5, -1.0, v2
	s_lshl_b32 s27, s0, 8
	v_mul_f32_e32 v0, v32, v0
	v_fma_f32 v5, v42, v5, 1.0
	s_add_i32 s1, s36, s27
	v_mul_f32_e32 v3, v5, v3
	v_mul_f32_e32 v0, v4, v0
	v_lshl_add_u32 v5, v37, 2, s1
	ds_write2st64_b32 v5, v0, v4 offset1:16
	v_mul_f32_e32 v0, v1, v2
	ds_write2st64_b32 v5, v0, v3 offset0:32 offset1:48
	v_lshlrev_b32_e32 v0, 16, v27
	v_lshlrev_b32_e32 v1, 16, v62
	s_lshl_b32 s25, s0, 3
	ds_write2st64_b32 v5, v0, v1 offset0:64 offset1:80
	s_and_saveexec_b64 s[0:1], s[2:3]
	s_add_i32 s36, s36, s25
	v_mov_b32_e32 v0, v29
	v_mov_b32_e32 v1, v30
	v_mov_b32_e32 v2, s36
	ds_write_b64 v2, v[0:1] offset:24576
	s_or_b64 exec, exec, s[0:1]
	s_or_b32 s0, s31, 16
	v_readlane_b32 s50, v253, 20
	s_add_i32 s48, s0, s50
	v_readlane_b32 s46, v254, 25
	s_lshl_b64 s[36:37], s[48:49], 10
	v_or3_b32 v1, s37, 0, 0
	v_mov_b32_e32 v28, s46
	v_or3_b32 v0, s36, v28, v37
	v_lshlrev_b64 v[0:1], 1, v[0:1]
	v_lshl_add_u64 v[2:3], s[4:5], 0, v[0:1]
	global_load_ushort v43, v[2:3], off
	v_lshl_add_u64 v[2:3], s[8:9], 0, v[0:1]
	s_lshl_b64 s[36:37], s[48:49], 8
	global_load_ushort v45, v[2:3], off
	v_lshl_add_u64 v[2:3], s[10:11], 0, v[0:1]
	s_add_u32 s36, s16, s36
	global_load_ushort v44, v[2:3], off
	v_lshl_add_u64 v[2:3], s[6:7], 0, v[0:1]
	v_lshl_add_u64 v[0:1], s[12:13], 0, v[0:1]
	s_addc_u32 s37, s17, s37
	v_readlane_b32 s47, v254, 26
	global_load_ushort v46, v[2:3], off
	global_load_ushort v49, v[0:1], off
	s_mov_b32 s40, 1
	global_load_dwordx4 v[0:3], v177, s[36:37]
	s_or_b32 s36, s48, 1
	s_mov_b32 s37, s49
	s_lshl_b64 s[46:47], s[36:37], 10
	v_or3_b32 v5, s47, 0, 0
	v_or3_b32 v4, s46, v28, v37
	v_lshlrev_b64 v[4:5], 1, v[4:5]
	v_lshl_add_u64 v[6:7], s[4:5], 0, v[4:5]
	global_load_ushort v3, v[6:7], off
	v_lshl_add_u64 v[6:7], s[8:9], 0, v[4:5]
	s_lshl_b64 s[36:37], s[36:37], 8
	global_load_ushort v52, v[6:7], off
	v_lshl_add_u64 v[6:7], s[10:11], 0, v[4:5]
	s_add_u32 s36, s16, s36
	global_load_ushort v47, v[6:7], off
	v_lshl_add_u64 v[6:7], s[6:7], 0, v[4:5]
	v_lshl_add_u64 v[4:5], s[12:13], 0, v[4:5]
	s_addc_u32 s37, s17, s37
	global_load_ushort v50, v[6:7], off
	global_load_ushort v53, v[4:5], off
	v_lshlrev_b32_e32 v36, 1, v36
	global_load_dwordx4 v[4:7], v177, s[36:37]
	s_or_b32 s36, s48, 2
	s_mov_b32 s37, s49
	s_lshl_b64 s[46:47], s[36:37], 10
	v_or3_b32 v9, s47, 0, 0
	v_or3_b32 v8, s46, v28, v37
	v_lshlrev_b64 v[8:9], 1, v[8:9]
	v_lshl_add_u64 v[10:11], s[4:5], 0, v[8:9]
	global_load_ushort v7, v[10:11], off
	v_lshl_add_u64 v[10:11], s[8:9], 0, v[8:9]
	s_lshl_b64 s[36:37], s[36:37], 8
	global_load_ushort v60, v[10:11], off
	v_lshl_add_u64 v[10:11], s[10:11], 0, v[8:9]
	s_add_u32 s36, s16, s36
	global_load_ushort v48, v[10:11], off
	v_lshl_add_u64 v[10:11], s[6:7], 0, v[8:9]
	v_lshl_add_u64 v[8:9], s[12:13], 0, v[8:9]
	s_addc_u32 s37, s17, s37
	global_load_ushort v51, v[10:11], off
	global_load_ushort v55, v[8:9], off
	s_nop 0
	global_load_dwordx4 v[8:11], v177, s[36:37]
	s_or_b32 s36, s48, 3
	s_mov_b32 s37, s49
	s_lshl_b64 s[46:47], s[36:37], 10
	v_or3_b32 v13, s47, 0, 0
	v_or3_b32 v12, s46, v28, v37
	v_lshlrev_b64 v[12:13], 1, v[12:13]
	v_lshl_add_u64 v[14:15], s[4:5], 0, v[12:13]
	global_load_ushort v11, v[14:15], off
	v_lshl_add_u64 v[14:15], s[8:9], 0, v[12:13]
	s_lshl_b64 s[36:37], s[36:37], 8
	global_load_ushort v64, v[14:15], off
	v_lshl_add_u64 v[14:15], s[10:11], 0, v[12:13]
	s_add_u32 s36, s16, s36
	global_load_ushort v54, v[14:15], off
	v_lshl_add_u64 v[14:15], s[6:7], 0, v[12:13]
	v_lshl_add_u64 v[12:13], s[12:13], 0, v[12:13]
	s_addc_u32 s37, s17, s37
	global_load_ushort v57, v[14:15], off
	global_load_ushort v58, v[12:13], off
	s_nop 0
	global_load_dwordx4 v[12:15], v177, s[36:37]
	s_or_b32 s36, s48, 4
	s_mov_b32 s37, s49
	s_lshl_b64 s[46:47], s[36:37], 10
	v_or3_b32 v17, s47, 0, 0
	v_or3_b32 v16, s46, v28, v37
	v_lshlrev_b64 v[16:17], 1, v[16:17]
	v_lshl_add_u64 v[18:19], s[4:5], 0, v[16:17]
	global_load_ushort v15, v[18:19], off
	v_lshl_add_u64 v[18:19], s[8:9], 0, v[16:17]
	s_lshl_b64 s[36:37], s[36:37], 8
	global_load_ushort v67, v[18:19], off
	v_lshl_add_u64 v[18:19], s[10:11], 0, v[16:17]
	s_add_u32 s36, s16, s36
	global_load_ushort v56, v[18:19], off
	v_lshl_add_u64 v[18:19], s[6:7], 0, v[16:17]
	v_lshl_add_u64 v[16:17], s[12:13], 0, v[16:17]
	s_addc_u32 s37, s17, s37
	global_load_ushort v61, v[18:19], off
	global_load_ushort v63, v[16:17], off
	s_nop 0
	global_load_dwordx4 v[16:19], v177, s[36:37]
	s_or_b32 s36, s48, 5
	s_mov_b32 s37, s49
	s_lshl_b64 s[46:47], s[36:37], 10
	v_or3_b32 v21, s47, 0, 0
	v_or3_b32 v20, s46, v28, v37
	v_lshlrev_b64 v[20:21], 1, v[20:21]
	v_lshl_add_u64 v[22:23], s[4:5], 0, v[20:21]
	global_load_ushort v19, v[22:23], off
	v_lshl_add_u64 v[22:23], s[8:9], 0, v[20:21]
	s_lshl_b64 s[36:37], s[36:37], 8
	global_load_ushort v72, v[22:23], off
	v_lshl_add_u64 v[22:23], s[10:11], 0, v[20:21]
	s_add_u32 s36, s16, s36
	global_load_ushort v59, v[22:23], off
	v_lshl_add_u64 v[22:23], s[6:7], 0, v[20:21]
	v_lshl_add_u64 v[20:21], s[12:13], 0, v[20:21]
	s_addc_u32 s37, s17, s37
	global_load_ushort v62, v[22:23], off
	global_load_ushort v66, v[20:21], off
	s_nop 0
	global_load_dwordx4 v[20:23], v177, s[36:37]
	s_or_b32 s36, s48, 6
	s_mov_b32 s37, s49
	s_lshl_b64 s[46:47], s[36:37], 10
	v_or3_b32 v25, s47, 0, 0
	v_or3_b32 v24, s46, v28, v37
	v_lshlrev_b64 v[24:25], 1, v[24:25]
	v_lshl_add_u64 v[26:27], s[4:5], 0, v[24:25]
	global_load_ushort v23, v[26:27], off
	v_lshl_add_u64 v[26:27], s[8:9], 0, v[24:25]
	s_lshl_b64 s[36:37], s[36:37], 8
	global_load_ushort v74, v[26:27], off
	v_lshl_add_u64 v[26:27], s[10:11], 0, v[24:25]
	s_add_u32 s36, s16, s36
	global_load_ushort v65, v[26:27], off
	v_lshl_add_u64 v[26:27], s[6:7], 0, v[24:25]
	v_lshl_add_u64 v[24:25], s[12:13], 0, v[24:25]
	s_addc_u32 s37, s17, s37
	s_or_b32 s48, s48, 7
	global_load_ushort v69, v[26:27], off
	global_load_ushort v71, v[24:25], off
	s_nop 0
	global_load_dwordx4 v[24:27], v177, s[36:37]
	s_lshl_b64 s[36:37], s[48:49], 10
	v_or3_b32 v29, s37, 0, 0
	v_or3_b32 v28, s36, v28, v37
	s_lshl_b64 s[36:37], s[48:49], 8
	s_add_u32 s36, s16, s36
	s_addc_u32 s37, s17, s37
	s_min_u32 s0, s0, 0x1ff7
	v_lshlrev_b64 v[28:29], 1, v[28:29]
	s_add_i32 s48, s0, s51
	v_lshl_add_u64 v[30:31], s[4:5], 0, v[28:29]
	s_lshl_b64 s[0:1], s[48:49], 11
	global_load_ushort v27, v[30:31], off
	v_lshl_add_u64 v[30:31], s[8:9], 0, v[28:29]
	s_add_u32 s0, s8, s0
	global_load_ushort v75, v[30:31], off
	v_lshl_add_u64 v[30:31], s[10:11], 0, v[28:29]
	s_addc_u32 s1, s9, s1
	global_load_ushort v68, v[30:31], off
	v_lshl_add_u64 v[30:31], s[6:7], 0, v[28:29]
	v_lshl_add_u64 v[28:29], s[12:13], 0, v[28:29]
	s_add_u32 s0, s0, s33
	global_load_ushort v70, v[30:31], off
	global_load_ushort v73, v[28:29], off
	s_addc_u32 s1, s1, 0
	global_load_dwordx4 v[28:31], v177, s[36:37]
	global_load_ushort v31, v176, s[0:1]
	s_lshl_b64 s[0:1], s[48:49], 8
	s_add_u32 s0, s16, s0
	s_addc_u32 s1, s17, s1
	global_load_dwordx4 v[32:35], v177, s[0:1]
	s_waitcnt lgkmcnt(0)
	s_barrier
	s_add_u32 s0, s8, s33
	s_addc_u32 s1, s9, 0
	s_add_i32 s29, s29, s30
	v_lshl_add_u64 v[38:39], s[0:1], 0, v[176:177]
	s_lshl_b32 s37, s28, 6
	s_lshl_b32 s36, s34, 3
	s_lshl_b32 s35, s35, 3
	s_lshl_b32 s34, s41, 3
	s_lshl_b32 s33, s42, 3
	s_lshl_b32 s31, s44, 3
	s_lshl_b32 s28, s45, 3
	s_add_i32 s30, s29, s50
	s_mov_b32 s41, 0
	s_branch .LBB0_630
.LBB0_629:
	s_or_b64 exec, exec, s[0:1]
	s_add_i32 s1, s30, s41
	s_add_i32 s48, s1, 32
	s_lshl_b64 s[44:45], s[48:49], 11
	v_or_b32_e32 v0, s44, v36
	v_mov_b32_e32 v1, s45
	s_add_i32 s0, s29, s41
	v_lshl_add_u64 v[2:3], s[4:5], 0, v[0:1]
	s_add_i32 s0, s0, 32
	global_load_ushort v43, v[2:3], off
	v_lshl_add_u64 v[2:3], s[8:9], 0, v[0:1]
	s_lshl_b64 s[44:45], s[48:49], 8
	global_load_ushort v45, v[2:3], off
	v_lshl_add_u64 v[2:3], s[10:11], 0, v[0:1]
	s_add_u32 s44, s16, s44
	global_load_ushort v44, v[2:3], off
	v_lshl_add_u64 v[2:3], s[6:7], 0, v[0:1]
	v_lshl_add_u64 v[0:1], s[12:13], 0, v[0:1]
	s_addc_u32 s45, s17, s45
	s_add_i32 s48, s1, 33
	global_load_ushort v46, v[2:3], off
	global_load_ushort v49, v[0:1], off
	s_nop 0
	global_load_dwordx4 v[0:3], v177, s[44:45]
	s_lshl_b64 s[44:45], s[48:49], 11
	v_or_b32_e32 v4, s44, v36
	v_mov_b32_e32 v5, s45
	v_lshl_add_u64 v[6:7], s[4:5], 0, v[4:5]
	global_load_ushort v3, v[6:7], off
	v_lshl_add_u64 v[6:7], s[8:9], 0, v[4:5]
	s_lshl_b64 s[44:45], s[48:49], 8
	global_load_ushort v52, v[6:7], off
	v_lshl_add_u64 v[6:7], s[10:11], 0, v[4:5]
	s_add_u32 s44, s16, s44
	global_load_ushort v47, v[6:7], off
	v_lshl_add_u64 v[6:7], s[6:7], 0, v[4:5]
	v_lshl_add_u64 v[4:5], s[12:13], 0, v[4:5]
	s_addc_u32 s45, s17, s45
	s_add_i32 s48, s1, 34
	global_load_ushort v50, v[6:7], off
	global_load_ushort v53, v[4:5], off
	s_nop 0
	global_load_dwordx4 v[4:7], v177, s[44:45]
	s_lshl_b64 s[44:45], s[48:49], 11
	v_or_b32_e32 v8, s44, v36
	v_mov_b32_e32 v9, s45
	v_lshl_add_u64 v[10:11], s[4:5], 0, v[8:9]
	global_load_ushort v7, v[10:11], off
	v_lshl_add_u64 v[10:11], s[8:9], 0, v[8:9]
	s_lshl_b64 s[44:45], s[48:49], 8
	global_load_ushort v60, v[10:11], off
	v_lshl_add_u64 v[10:11], s[10:11], 0, v[8:9]
	s_add_u32 s44, s16, s44
	global_load_ushort v48, v[10:11], off
	v_lshl_add_u64 v[10:11], s[6:7], 0, v[8:9]
	v_lshl_add_u64 v[8:9], s[12:13], 0, v[8:9]
	s_addc_u32 s45, s17, s45
	s_add_i32 s48, s1, 35
	global_load_ushort v51, v[10:11], off
	global_load_ushort v55, v[8:9], off
	s_nop 0
	global_load_dwordx4 v[8:11], v177, s[44:45]
	s_lshl_b64 s[44:45], s[48:49], 11
	v_or_b32_e32 v12, s44, v36
	v_mov_b32_e32 v13, s45
	v_lshl_add_u64 v[14:15], s[4:5], 0, v[12:13]
	global_load_ushort v11, v[14:15], off
	v_lshl_add_u64 v[14:15], s[8:9], 0, v[12:13]
	s_lshl_b64 s[44:45], s[48:49], 8
	global_load_ushort v64, v[14:15], off
	v_lshl_add_u64 v[14:15], s[10:11], 0, v[12:13]
	s_add_u32 s44, s16, s44
	global_load_ushort v54, v[14:15], off
	v_lshl_add_u64 v[14:15], s[6:7], 0, v[12:13]
	v_lshl_add_u64 v[12:13], s[12:13], 0, v[12:13]
	s_addc_u32 s45, s17, s45
	s_add_i32 s48, s1, 36
	global_load_ushort v57, v[14:15], off
	global_load_ushort v58, v[12:13], off
	s_nop 0
	global_load_dwordx4 v[12:15], v177, s[44:45]
	s_lshl_b64 s[44:45], s[48:49], 11
	v_or_b32_e32 v16, s44, v36
	v_mov_b32_e32 v17, s45
	v_lshl_add_u64 v[18:19], s[4:5], 0, v[16:17]
	global_load_ushort v15, v[18:19], off
	v_lshl_add_u64 v[18:19], s[8:9], 0, v[16:17]
	s_lshl_b64 s[44:45], s[48:49], 8
	global_load_ushort v67, v[18:19], off
	v_lshl_add_u64 v[18:19], s[10:11], 0, v[16:17]
	s_add_u32 s44, s16, s44
	global_load_ushort v56, v[18:19], off
	v_lshl_add_u64 v[18:19], s[6:7], 0, v[16:17]
	v_lshl_add_u64 v[16:17], s[12:13], 0, v[16:17]
	s_addc_u32 s45, s17, s45
	s_add_i32 s48, s1, 37
	global_load_ushort v61, v[18:19], off
	global_load_ushort v63, v[16:17], off
	s_nop 0
	global_load_dwordx4 v[16:19], v177, s[44:45]
	s_lshl_b64 s[44:45], s[48:49], 11
	v_or_b32_e32 v20, s44, v36
	v_mov_b32_e32 v21, s45
	v_lshl_add_u64 v[22:23], s[4:5], 0, v[20:21]
	global_load_ushort v19, v[22:23], off
	v_lshl_add_u64 v[22:23], s[8:9], 0, v[20:21]
	s_lshl_b64 s[44:45], s[48:49], 8
	global_load_ushort v72, v[22:23], off
	v_lshl_add_u64 v[22:23], s[10:11], 0, v[20:21]
	s_add_u32 s44, s16, s44
	global_load_ushort v59, v[22:23], off
	v_lshl_add_u64 v[22:23], s[6:7], 0, v[20:21]
	v_lshl_add_u64 v[20:21], s[12:13], 0, v[20:21]
	s_addc_u32 s45, s17, s45
	s_add_i32 s48, s1, 38
	global_load_ushort v62, v[22:23], off
	global_load_ushort v66, v[20:21], off
	s_nop 0
	global_load_dwordx4 v[20:23], v177, s[44:45]
	s_lshl_b64 s[44:45], s[48:49], 11
	v_or_b32_e32 v24, s44, v36
	v_mov_b32_e32 v25, s45
	v_lshl_add_u64 v[26:27], s[4:5], 0, v[24:25]
	global_load_ushort v23, v[26:27], off
	v_lshl_add_u64 v[26:27], s[8:9], 0, v[24:25]
	s_lshl_b64 s[44:45], s[48:49], 8
	global_load_ushort v74, v[26:27], off
	v_lshl_add_u64 v[26:27], s[10:11], 0, v[24:25]
	s_add_u32 s44, s16, s44
	global_load_ushort v65, v[26:27], off
	v_lshl_add_u64 v[26:27], s[6:7], 0, v[24:25]
	v_lshl_add_u64 v[24:25], s[12:13], 0, v[24:25]
	s_addc_u32 s45, s17, s45
	s_add_i32 s48, s1, 39
	global_load_ushort v69, v[26:27], off
	global_load_ushort v71, v[24:25], off
	s_nop 0
	global_load_dwordx4 v[24:27], v177, s[44:45]
	s_lshl_b64 s[44:45], s[48:49], 11
	v_or_b32_e32 v28, s44, v36
	v_mov_b32_e32 v29, s45
	s_lshl_b64 s[44:45], s[48:49], 8
	s_add_u32 s44, s16, s44
	s_addc_u32 s45, s17, s45
	s_min_i32 s0, s0, 0x1ff7
	v_lshl_add_u64 v[30:31], s[4:5], 0, v[28:29]
	s_add_i32 s48, s0, s51
	global_load_ushort v27, v[30:31], off
	v_lshl_add_u64 v[30:31], s[8:9], 0, v[28:29]
	s_lshl_b64 s[0:1], s[48:49], 11
	global_load_ushort v75, v[30:31], off
	v_lshl_add_u64 v[30:31], s[10:11], 0, v[28:29]
	v_lshl_add_u64 v[32:33], v[38:39], 0, s[0:1]
	s_lshl_b64 s[0:1], s[48:49], 8
	global_load_ushort v68, v[30:31], off
	v_lshl_add_u64 v[30:31], s[6:7], 0, v[28:29]
	v_lshl_add_u64 v[28:29], s[12:13], 0, v[28:29]
	s_add_u32 s0, s16, s0
	global_load_ushort v70, v[30:31], off
	global_load_ushort v73, v[28:29], off
	s_addc_u32 s1, s17, s1
	global_load_dwordx4 v[28:31], v177, s[44:45]
	global_load_ushort v31, v[32:33], off
	s_add_i32 s41, s41, 16
	global_load_dwordx4 v[32:35], v177, s[0:1]
	s_waitcnt lgkmcnt(0)
	s_barrier
	s_add_i32 s40, s40, 1
	s_cmpk_eq_i32 s41, 0xfe0
	s_cbranch_scc1 .LBB0_646
.LBB0_630:
	s_waitcnt vmcnt(0)
	v_lshlrev_b32_e32 v34, 16, v49
	s_and_b32 s0, s40, 1
	v_lshlrev_b32_e32 v33, 16, v45
	v_lshlrev_b32_e32 v35, 16, v46
	v_add_f32_e32 v45, -1.0, v34
	s_or_b32 s0, s0, s20
	v_mul_f32_e32 v35, 0xbfb8aa3b, v35
	v_fma_f32 v45, v42, v45, 1.0
	s_mulk_i32 s0, 0x6080
	v_exp_f32_e32 v35, v35
	v_mul_f32_e32 v45, v45, v33
	v_mul_f32_e32 v33, v41, v33
	s_add_i32 s42, s0, 0
	v_mul_f32_e32 v0, v0, v33
	v_lshlrev_b32_e32 v33, 16, v52
	v_mul_f32_e32 v46, v41, v33
	s_add_i32 s0, s42, s18
	v_mul_f32_e32 v4, v46, v4
	v_lshl_add_u32 v49, v37, 2, s0
	v_mul_f32_e32 v0, v0, v34
	v_mul_f32_e32 v46, v4, v35
	ds_write2st64_b32 v49, v0, v45 offset0:32 offset1:48
	v_lshlrev_b32_e32 v0, 16, v43
	v_lshlrev_b32_e32 v34, 16, v44
	ds_write2st64_b32 v49, v46, v35 offset1:16
	ds_write2st64_b32 v49, v0, v34 offset0:64 offset1:80
	s_and_saveexec_b64 s[0:1], s[2:3]
	s_add_i32 s44, s42, s37
	v_mov_b32_e32 v0, v1
	v_mov_b32_e32 v1, v2
	v_mov_b32_e32 v2, s44
	ds_write_b64 v2, v[0:1] offset:24576
	s_or_b64 exec, exec, s[0:1]
	v_lshlrev_b32_e32 v2, 16, v60
	v_mul_f32_e32 v0, v41, v2
	v_mul_f32_e32 v0, v0, v8
	v_lshlrev_b32_e32 v8, 16, v50
	v_mul_f32_e32 v8, 0xbfb8aa3b, v8
	v_lshlrev_b32_e32 v1, 16, v53
	v_exp_f32_e32 v8, v8
	v_add_f32_e32 v34, -1.0, v1
	v_fma_f32 v34, v42, v34, 1.0
	s_add_i32 s0, s42, s19
	v_mul_f32_e32 v33, v34, v33
	v_lshl_add_u32 v35, v37, 2, s0
	v_mul_f32_e32 v1, v4, v1
	v_mul_f32_e32 v34, v0, v8
	ds_write2st64_b32 v35, v1, v33 offset0:32 offset1:48
	v_lshlrev_b32_e32 v1, 16, v3
	v_lshlrev_b32_e32 v3, 16, v47
	ds_write2st64_b32 v35, v34, v8 offset1:16
	ds_write2st64_b32 v35, v1, v3 offset0:64 offset1:80
	s_and_saveexec_b64 s[0:1], s[2:3]
	s_add_i32 s44, s42, s36
	v_mov_b32_e32 v4, v5
	v_mov_b32_e32 v5, v6
	v_mov_b32_e32 v1, s44
	ds_write_b64 v1, v[4:5] offset:24576
	s_or_b64 exec, exec, s[0:1]
	v_lshlrev_b32_e32 v5, 16, v51
	v_mul_f32_e32 v5, 0xbfb8aa3b, v5
	v_lshlrev_b32_e32 v4, 16, v55
	v_exp_f32_e32 v5, v5
	v_lshlrev_b32_e32 v3, 16, v64
	v_add_f32_e32 v6, -1.0, v4
	v_mul_f32_e32 v1, v41, v3
	v_fma_f32 v6, v42, v6, 1.0
	s_add_i32 s0, s42, s21
	v_mul_f32_e32 v1, v1, v12
	v_mul_f32_e32 v2, v6, v2
	v_lshl_add_u32 v8, v37, 2, s0
	v_mul_f32_e32 v0, v0, v4
	v_mul_f32_e32 v6, v1, v5
	ds_write2st64_b32 v8, v0, v2 offset0:32 offset1:48
	v_lshlrev_b32_e32 v0, 16, v7
	v_lshlrev_b32_e32 v2, 16, v48
	ds_write2st64_b32 v8, v6, v5 offset1:16
	ds_write2st64_b32 v8, v0, v2 offset0:64 offset1:80
	s_and_saveexec_b64 s[0:1], s[2:3]
	s_add_i32 s44, s42, s35
	v_mov_b32_e32 v4, v9
	v_mov_b32_e32 v5, v10
	v_mov_b32_e32 v0, s44
	ds_write_b64 v0, v[4:5] offset:24576
	s_or_b64 exec, exec, s[0:1]
	v_lshlrev_b32_e32 v5, 16, v57
	v_mul_f32_e32 v5, 0xbfb8aa3b, v5
	v_lshlrev_b32_e32 v4, 16, v58
	v_exp_f32_e32 v5, v5
	v_lshlrev_b32_e32 v2, 16, v67
	v_add_f32_e32 v6, -1.0, v4
	v_mul_f32_e32 v0, v41, v2
	v_fma_f32 v6, v42, v6, 1.0
	s_add_i32 s0, s42, s22
	v_mul_f32_e32 v0, v0, v16
	v_mul_f32_e32 v3, v6, v3
	v_lshl_add_u32 v7, v37, 2, s0
	v_mul_f32_e32 v1, v1, v4
	v_mul_f32_e32 v6, v0, v5
	ds_write2st64_b32 v7, v1, v3 offset0:32 offset1:48
	v_lshlrev_b32_e32 v1, 16, v11
	v_lshlrev_b32_e32 v3, 16, v54
	ds_write2st64_b32 v7, v6, v5 offset1:16
	ds_write2st64_b32 v7, v1, v3 offset0:64 offset1:80
	s_and_saveexec_b64 s[0:1], s[2:3]
	s_add_i32 s44, s42, s34
	v_mov_b32_e32 v4, v13
	v_mov_b32_e32 v5, v14
	v_mov_b32_e32 v1, s44
	ds_write_b64 v1, v[4:5] offset:24576
	s_or_b64 exec, exec, s[0:1]
	v_lshlrev_b32_e32 v5, 16, v61
	v_mul_f32_e32 v5, 0xbfb8aa3b, v5
	v_lshlrev_b32_e32 v4, 16, v63
	v_exp_f32_e32 v5, v5
	v_lshlrev_b32_e32 v3, 16, v72
	v_add_f32_e32 v6, -1.0, v4
	v_mul_f32_e32 v1, v41, v3
	v_fma_f32 v6, v42, v6, 1.0
	s_add_i32 s0, s42, s23
	v_mul_f32_e32 v1, v1, v20
	v_mul_f32_e32 v2, v6, v2
	v_lshl_add_u32 v7, v37, 2, s0
	v_mul_f32_e32 v0, v0, v4
	v_mul_f32_e32 v6, v1, v5
	ds_write2st64_b32 v7, v0, v2 offset0:32 offset1:48
	v_lshlrev_b32_e32 v0, 16, v15
	v_lshlrev_b32_e32 v2, 16, v56
	ds_write2st64_b32 v7, v6, v5 offset1:16
	ds_write2st64_b32 v7, v0, v2 offset0:64 offset1:80
	s_and_saveexec_b64 s[0:1], s[2:3]
	s_add_i32 s44, s42, s33
	v_mov_b32_e32 v4, v17
	v_mov_b32_e32 v5, v18
	v_mov_b32_e32 v0, s44
	ds_write_b64 v0, v[4:5] offset:24576
	s_or_b64 exec, exec, s[0:1]
	v_lshlrev_b32_e32 v5, 16, v62
	v_mul_f32_e32 v5, 0xbfb8aa3b, v5
	v_lshlrev_b32_e32 v4, 16, v66
	v_exp_f32_e32 v5, v5
	v_lshlrev_b32_e32 v2, 16, v74
	v_add_f32_e32 v6, -1.0, v4
	v_mul_f32_e32 v0, v41, v2
	v_fma_f32 v6, v42, v6, 1.0
	s_add_i32 s0, s42, s24
	v_mul_f32_e32 v0, v0, v24
	v_mul_f32_e32 v3, v6, v3
	v_lshl_add_u32 v7, v37, 2, s0
	v_mul_f32_e32 v1, v1, v4
	v_mul_f32_e32 v6, v0, v5
	ds_write2st64_b32 v7, v1, v3 offset0:32 offset1:48
	v_lshlrev_b32_e32 v1, 16, v19
	v_lshlrev_b32_e32 v3, 16, v59
	ds_write2st64_b32 v7, v6, v5 offset1:16
	ds_write2st64_b32 v7, v1, v3 offset0:64 offset1:80
	s_and_saveexec_b64 s[0:1], s[2:3]
	s_add_i32 s44, s42, s31
	v_mov_b32_e32 v4, v21
	v_mov_b32_e32 v5, v22
	v_mov_b32_e32 v1, s44
	ds_write_b64 v1, v[4:5] offset:24576
	s_or_b64 exec, exec, s[0:1]
	v_lshlrev_b32_e32 v5, 16, v69
	v_mul_f32_e32 v5, 0xbfb8aa3b, v5
	v_lshlrev_b32_e32 v4, 16, v71
	v_exp_f32_e32 v5, v5
	v_lshlrev_b32_e32 v3, 16, v75
	v_add_f32_e32 v6, -1.0, v4
	v_mul_f32_e32 v1, v41, v3
	v_fma_f32 v6, v42, v6, 1.0
	s_add_i32 s0, s42, s26
	v_mul_f32_e32 v1, v1, v28
	v_mul_f32_e32 v2, v6, v2
	v_lshl_add_u32 v7, v37, 2, s0
	v_mul_f32_e32 v0, v0, v4
	v_mul_f32_e32 v6, v1, v5
	ds_write2st64_b32 v7, v0, v2 offset0:32 offset1:48
	v_lshlrev_b32_e32 v0, 16, v23
	v_lshlrev_b32_e32 v2, 16, v65
	ds_write2st64_b32 v7, v6, v5 offset1:16
	ds_write2st64_b32 v7, v0, v2 offset0:64 offset1:80
	s_and_saveexec_b64 s[0:1], s[2:3]
	s_add_i32 s44, s42, s28
	v_mov_b32_e32 v4, v25
	v_mov_b32_e32 v5, v26
	v_mov_b32_e32 v0, s44
	ds_write_b64 v0, v[4:5] offset:24576
	s_or_b64 exec, exec, s[0:1]
	v_lshlrev_b32_e32 v4, 16, v70
	v_mul_f32_e32 v4, 0xbfb8aa3b, v4
	v_exp_f32_e32 v4, v4
	v_lshlrev_b32_e32 v0, 16, v31
	v_lshlrev_b32_e32 v2, 16, v73
	v_mul_f32_e32 v0, v41, v0
	v_add_f32_e32 v5, -1.0, v2
	v_mul_f32_e32 v0, v0, v32
	v_fma_f32 v5, v42, v5, 1.0
	s_add_i32 s0, s42, s27
	v_mul_f32_e32 v3, v5, v3
	v_mul_f32_e32 v0, v0, v4
	v_lshl_add_u32 v5, v37, 2, s0
	ds_write2st64_b32 v5, v0, v4 offset1:16
	v_mul_f32_e32 v0, v1, v2
	ds_write2st64_b32 v5, v0, v3 offset0:32 offset1:48
	v_lshlrev_b32_e32 v0, 16, v27
	v_lshlrev_b32_e32 v1, 16, v68
	ds_write2st64_b32 v5, v0, v1 offset0:64 offset1:80
	s_and_saveexec_b64 s[0:1], s[2:3]
	s_cbranch_execz .LBB0_629
	s_add_i32 s42, s42, s25
	v_mov_b32_e32 v0, v29
	v_mov_b32_e32 v1, v30
	v_mov_b32_e32 v2, s42
	ds_write_b64 v2, v[0:1] offset:24576
	s_branch .LBB0_629
